# static priority raise variant: s_setprio 1 for waves 0-3 (the other half) during the attention chunk loops; on top of v64
# speedup vs baseline: 1.0058x; 1.0023x over previous
.LBB0_247:
	v_readfirstlane_b32 s98, v182
	s_nop 3
	s_lshr_b32 s98, s98, 6
	s_cmp_lt_u32 s98, 4
	s_cbranch_scc0 .Lprio_done_a
	s_setprio 1
